# down-projection sample-row split-K units: hand-scheduled K loop (3-slot register ring, 16 loads in flight) instead of hipcc's load->wait->MFMA chain
# speedup vs baseline: 1.0067x; 1.0034x over previous
.LBB0_1257:
	s_and_b32 s36, s6, 0xc0
	s_and_b32 s37, s4, 0xffffffc0
	v_or_b32_e32 v0, s36, v76
	v_lshlrev_b32_e32 v192, 13, v0
	v_or_b32_e32 v0, s37, v76
	v_lshl_add_u64 v[68:69], v[64:65], 0, v[192:193]
	v_ashrrev_i32_e32 v1, 31, v0
	v_lshlrev_b64 v[0:1], 13, v[0:1]
	v_lshl_add_u64 v[72:73], v[66:67], 0, v[0:1]
	v_add_co_u32_e32 v70, vcc, 0x40000, v72
	s_nop 1
	v_addc_co_u32_e32 v71, vcc, 0, v73, vcc
	v_add_co_u32_e32 v74, vcc, 0x40000, v68
	s_nop 1
	v_addc_co_u32_e32 v75, vcc, 0, v69, vcc
	global_load_dwordx4 v[92:95], v[68:69], off
	global_load_dwordx4 v[96:99], v[68:69], off offset:32
	global_load_dwordx4 v[100:103], v[74:75], off
	global_load_dwordx4 v[104:107], v[74:75], off offset:32
	global_load_dwordx4 v[108:111], v[72:73], off
	global_load_dwordx4 v[112:115], v[72:73], off offset:32
	global_load_dwordx4 v[116:119], v[70:71], off
	global_load_dwordx4 v[120:123], v[70:71], off offset:32
	global_load_dwordx4 v[124:127], v[68:69], off offset:64
	global_load_dwordx4 v[128:131], v[68:69], off offset:96
	global_load_dwordx4 v[132:135], v[74:75], off offset:64
	global_load_dwordx4 v[136:139], v[74:75], off offset:96
	global_load_dwordx4 v[144:147], v[72:73], off offset:64
	global_load_dwordx4 v[148:151], v[72:73], off offset:96
	global_load_dwordx4 v[152:155], v[70:71], off offset:64
	global_load_dwordx4 v[156:159], v[70:71], off offset:96
	global_load_dwordx4 v[160:163], v[68:69], off offset:128
	global_load_dwordx4 v[164:167], v[68:69], off offset:160
	global_load_dwordx4 v[168:171], v[74:75], off offset:128
	global_load_dwordx4 v[172:175], v[74:75], off offset:160
	global_load_dwordx4 v[176:179], v[72:73], off offset:128
	global_load_dwordx4 v[180:183], v[72:73], off offset:160
	global_load_dwordx4 v[184:187], v[70:71], off offset:128
	global_load_dwordx4 v[188:191], v[70:71], off offset:160
	s_waitcnt vmcnt(16)
	v_mfma_f32_32x32x16_bf16 v[0:15], v[92:95], v[108:111], 0
	v_mfma_f32_32x32x16_bf16 v[48:63], v[92:95], v[116:119], 0
	v_mfma_f32_32x32x16_bf16 v[16:31], v[100:103], v[108:111], 0
	v_mfma_f32_32x32x16_bf16 v[32:47], v[100:103], v[116:119], 0
	v_mfma_f32_32x32x16_bf16 v[0:15], v[96:99], v[112:115], v[0:15]
	v_mfma_f32_32x32x16_bf16 v[48:63], v[96:99], v[120:123], v[48:63]
	v_mfma_f32_32x32x16_bf16 v[16:31], v[104:107], v[112:115], v[16:31]
	v_mfma_f32_32x32x16_bf16 v[32:47], v[104:107], v[120:123], v[32:47]
	global_load_dwordx4 v[92:95], v[68:69], off offset:192
	global_load_dwordx4 v[96:99], v[68:69], off offset:224
	global_load_dwordx4 v[100:103], v[74:75], off offset:192
	global_load_dwordx4 v[104:107], v[74:75], off offset:224
	global_load_dwordx4 v[108:111], v[72:73], off offset:192
	global_load_dwordx4 v[112:115], v[72:73], off offset:224
	global_load_dwordx4 v[116:119], v[70:71], off offset:192
	global_load_dwordx4 v[120:123], v[70:71], off offset:224
	s_waitcnt vmcnt(16)
	v_mfma_f32_32x32x16_bf16 v[0:15], v[124:127], v[144:147], v[0:15]
	v_mfma_f32_32x32x16_bf16 v[48:63], v[124:127], v[152:155], v[48:63]
	v_mfma_f32_32x32x16_bf16 v[16:31], v[132:135], v[144:147], v[16:31]
	v_mfma_f32_32x32x16_bf16 v[32:47], v[132:135], v[152:155], v[32:47]
	v_mfma_f32_32x32x16_bf16 v[0:15], v[128:131], v[148:151], v[0:15]
	v_mfma_f32_32x32x16_bf16 v[48:63], v[128:131], v[156:159], v[48:63]
	v_mfma_f32_32x32x16_bf16 v[16:31], v[136:139], v[148:151], v[16:31]
	v_mfma_f32_32x32x16_bf16 v[32:47], v[136:139], v[156:159], v[32:47]
	global_load_dwordx4 v[124:127], v[68:69], off offset:256
	global_load_dwordx4 v[128:131], v[68:69], off offset:288
	global_load_dwordx4 v[132:135], v[74:75], off offset:256
	global_load_dwordx4 v[136:139], v[74:75], off offset:288
	global_load_dwordx4 v[144:147], v[72:73], off offset:256
	global_load_dwordx4 v[148:151], v[72:73], off offset:288
	global_load_dwordx4 v[152:155], v[70:71], off offset:256
	global_load_dwordx4 v[156:159], v[70:71], off offset:288
	s_waitcnt vmcnt(16)
	v_mfma_f32_32x32x16_bf16 v[0:15], v[160:163], v[176:179], v[0:15]
	v_mfma_f32_32x32x16_bf16 v[48:63], v[160:163], v[184:187], v[48:63]
	v_mfma_f32_32x32x16_bf16 v[16:31], v[168:171], v[176:179], v[16:31]
	v_mfma_f32_32x32x16_bf16 v[32:47], v[168:171], v[184:187], v[32:47]
	v_mfma_f32_32x32x16_bf16 v[0:15], v[164:167], v[180:183], v[0:15]
	v_mfma_f32_32x32x16_bf16 v[48:63], v[164:167], v[188:191], v[48:63]
	v_mfma_f32_32x32x16_bf16 v[16:31], v[172:175], v[180:183], v[16:31]
	v_mfma_f32_32x32x16_bf16 v[32:47], v[172:175], v[188:191], v[32:47]
	global_load_dwordx4 v[160:163], v[68:69], off offset:320
	global_load_dwordx4 v[164:167], v[68:69], off offset:352
	global_load_dwordx4 v[168:171], v[74:75], off offset:320
	global_load_dwordx4 v[172:175], v[74:75], off offset:352
	global_load_dwordx4 v[176:179], v[72:73], off offset:320
	global_load_dwordx4 v[180:183], v[72:73], off offset:352
	global_load_dwordx4 v[184:187], v[70:71], off offset:320
	global_load_dwordx4 v[188:191], v[70:71], off offset:352
	s_waitcnt vmcnt(16)
	v_mfma_f32_32x32x16_bf16 v[0:15], v[92:95], v[108:111], v[0:15]
	v_mfma_f32_32x32x16_bf16 v[48:63], v[92:95], v[116:119], v[48:63]
	v_mfma_f32_32x32x16_bf16 v[16:31], v[100:103], v[108:111], v[16:31]
	v_mfma_f32_32x32x16_bf16 v[32:47], v[100:103], v[116:119], v[32:47]
	v_mfma_f32_32x32x16_bf16 v[0:15], v[96:99], v[112:115], v[0:15]
	v_mfma_f32_32x32x16_bf16 v[48:63], v[96:99], v[120:123], v[48:63]
	v_mfma_f32_32x32x16_bf16 v[16:31], v[104:107], v[112:115], v[16:31]
	v_mfma_f32_32x32x16_bf16 v[32:47], v[104:107], v[120:123], v[32:47]
	global_load_dwordx4 v[92:95], v[68:69], off offset:384
	global_load_dwordx4 v[96:99], v[68:69], off offset:416
	global_load_dwordx4 v[100:103], v[74:75], off offset:384
	global_load_dwordx4 v[104:107], v[74:75], off offset:416
	global_load_dwordx4 v[108:111], v[72:73], off offset:384
	global_load_dwordx4 v[112:115], v[72:73], off offset:416
	global_load_dwordx4 v[116:119], v[70:71], off offset:384
	global_load_dwordx4 v[120:123], v[70:71], off offset:416
	s_waitcnt vmcnt(16)
	v_mfma_f32_32x32x16_bf16 v[0:15], v[124:127], v[144:147], v[0:15]
	v_mfma_f32_32x32x16_bf16 v[48:63], v[124:127], v[152:155], v[48:63]
	v_mfma_f32_32x32x16_bf16 v[16:31], v[132:135], v[144:147], v[16:31]
	v_mfma_f32_32x32x16_bf16 v[32:47], v[132:135], v[152:155], v[32:47]
	v_mfma_f32_32x32x16_bf16 v[0:15], v[128:131], v[148:151], v[0:15]
	v_mfma_f32_32x32x16_bf16 v[48:63], v[128:131], v[156:159], v[48:63]
	v_mfma_f32_32x32x16_bf16 v[16:31], v[136:139], v[148:151], v[16:31]
	v_mfma_f32_32x32x16_bf16 v[32:47], v[136:139], v[156:159], v[32:47]
	global_load_dwordx4 v[124:127], v[68:69], off offset:448
	global_load_dwordx4 v[128:131], v[68:69], off offset:480
	global_load_dwordx4 v[132:135], v[74:75], off offset:448
	global_load_dwordx4 v[136:139], v[74:75], off offset:480
	global_load_dwordx4 v[144:147], v[72:73], off offset:448
	global_load_dwordx4 v[148:151], v[72:73], off offset:480
	global_load_dwordx4 v[152:155], v[70:71], off offset:448
	global_load_dwordx4 v[156:159], v[70:71], off offset:480
	s_waitcnt vmcnt(16)
	v_mfma_f32_32x32x16_bf16 v[0:15], v[160:163], v[176:179], v[0:15]
	v_mfma_f32_32x32x16_bf16 v[48:63], v[160:163], v[184:187], v[48:63]
	v_mfma_f32_32x32x16_bf16 v[16:31], v[168:171], v[176:179], v[16:31]
	v_mfma_f32_32x32x16_bf16 v[32:47], v[168:171], v[184:187], v[32:47]
	v_mfma_f32_32x32x16_bf16 v[0:15], v[164:167], v[180:183], v[0:15]
	v_mfma_f32_32x32x16_bf16 v[48:63], v[164:167], v[188:191], v[48:63]
	v_mfma_f32_32x32x16_bf16 v[16:31], v[172:175], v[180:183], v[16:31]
	v_mfma_f32_32x32x16_bf16 v[32:47], v[172:175], v[188:191], v[32:47]
	global_load_dwordx4 v[160:163], v[68:69], off offset:512
	global_load_dwordx4 v[164:167], v[68:69], off offset:544
	global_load_dwordx4 v[168:171], v[74:75], off offset:512
	global_load_dwordx4 v[172:175], v[74:75], off offset:544
	global_load_dwordx4 v[176:179], v[72:73], off offset:512
	global_load_dwordx4 v[180:183], v[72:73], off offset:544
	global_load_dwordx4 v[184:187], v[70:71], off offset:512
	global_load_dwordx4 v[188:191], v[70:71], off offset:544
	s_waitcnt vmcnt(16)
	v_mfma_f32_32x32x16_bf16 v[0:15], v[92:95], v[108:111], v[0:15]
	v_mfma_f32_32x32x16_bf16 v[48:63], v[92:95], v[116:119], v[48:63]
	v_mfma_f32_32x32x16_bf16 v[16:31], v[100:103], v[108:111], v[16:31]
	v_mfma_f32_32x32x16_bf16 v[32:47], v[100:103], v[116:119], v[32:47]
	v_mfma_f32_32x32x16_bf16 v[0:15], v[96:99], v[112:115], v[0:15]
	v_mfma_f32_32x32x16_bf16 v[48:63], v[96:99], v[120:123], v[48:63]
	v_mfma_f32_32x32x16_bf16 v[16:31], v[104:107], v[112:115], v[16:31]
	v_mfma_f32_32x32x16_bf16 v[32:47], v[104:107], v[120:123], v[32:47]
	global_load_dwordx4 v[92:95], v[68:69], off offset:576
	global_load_dwordx4 v[96:99], v[68:69], off offset:608
	global_load_dwordx4 v[100:103], v[74:75], off offset:576
	global_load_dwordx4 v[104:107], v[74:75], off offset:608
	global_load_dwordx4 v[108:111], v[72:73], off offset:576
	global_load_dwordx4 v[112:115], v[72:73], off offset:608
	global_load_dwordx4 v[116:119], v[70:71], off offset:576
	global_load_dwordx4 v[120:123], v[70:71], off offset:608
	s_waitcnt vmcnt(16)
	v_mfma_f32_32x32x16_bf16 v[0:15], v[124:127], v[144:147], v[0:15]
	v_mfma_f32_32x32x16_bf16 v[48:63], v[124:127], v[152:155], v[48:63]
	v_mfma_f32_32x32x16_bf16 v[16:31], v[132:135], v[144:147], v[16:31]
	v_mfma_f32_32x32x16_bf16 v[32:47], v[132:135], v[152:155], v[32:47]
	v_mfma_f32_32x32x16_bf16 v[0:15], v[128:131], v[148:151], v[0:15]
	v_mfma_f32_32x32x16_bf16 v[48:63], v[128:131], v[156:159], v[48:63]
	v_mfma_f32_32x32x16_bf16 v[16:31], v[136:139], v[148:151], v[16:31]
	v_mfma_f32_32x32x16_bf16 v[32:47], v[136:139], v[156:159], v[32:47]
	global_load_dwordx4 v[124:127], v[68:69], off offset:640
	global_load_dwordx4 v[128:131], v[68:69], off offset:672
	global_load_dwordx4 v[132:135], v[74:75], off offset:640
	global_load_dwordx4 v[136:139], v[74:75], off offset:672
	global_load_dwordx4 v[144:147], v[72:73], off offset:640
	global_load_dwordx4 v[148:151], v[72:73], off offset:672
	global_load_dwordx4 v[152:155], v[70:71], off offset:640
	global_load_dwordx4 v[156:159], v[70:71], off offset:672
	s_waitcnt vmcnt(16)
	v_mfma_f32_32x32x16_bf16 v[0:15], v[160:163], v[176:179], v[0:15]
	v_mfma_f32_32x32x16_bf16 v[48:63], v[160:163], v[184:187], v[48:63]
	v_mfma_f32_32x32x16_bf16 v[16:31], v[168:171], v[176:179], v[16:31]
	v_mfma_f32_32x32x16_bf16 v[32:47], v[168:171], v[184:187], v[32:47]
	v_mfma_f32_32x32x16_bf16 v[0:15], v[164:167], v[180:183], v[0:15]
	v_mfma_f32_32x32x16_bf16 v[48:63], v[164:167], v[188:191], v[48:63]
	v_mfma_f32_32x32x16_bf16 v[16:31], v[172:175], v[180:183], v[16:31]
	v_mfma_f32_32x32x16_bf16 v[32:47], v[172:175], v[188:191], v[32:47]
	global_load_dwordx4 v[160:163], v[68:69], off offset:704
	global_load_dwordx4 v[164:167], v[68:69], off offset:736
	global_load_dwordx4 v[168:171], v[74:75], off offset:704
	global_load_dwordx4 v[172:175], v[74:75], off offset:736
	global_load_dwordx4 v[176:179], v[72:73], off offset:704
	global_load_dwordx4 v[180:183], v[72:73], off offset:736
	global_load_dwordx4 v[184:187], v[70:71], off offset:704
	global_load_dwordx4 v[188:191], v[70:71], off offset:736
	s_waitcnt vmcnt(16)
	v_mfma_f32_32x32x16_bf16 v[0:15], v[92:95], v[108:111], v[0:15]
	v_mfma_f32_32x32x16_bf16 v[48:63], v[92:95], v[116:119], v[48:63]
	v_mfma_f32_32x32x16_bf16 v[16:31], v[100:103], v[108:111], v[16:31]
	v_mfma_f32_32x32x16_bf16 v[32:47], v[100:103], v[116:119], v[32:47]
	v_mfma_f32_32x32x16_bf16 v[0:15], v[96:99], v[112:115], v[0:15]
	v_mfma_f32_32x32x16_bf16 v[48:63], v[96:99], v[120:123], v[48:63]
	v_mfma_f32_32x32x16_bf16 v[16:31], v[104:107], v[112:115], v[16:31]
	v_mfma_f32_32x32x16_bf16 v[32:47], v[104:107], v[120:123], v[32:47]
	global_load_dwordx4 v[92:95], v[68:69], off offset:768
	global_load_dwordx4 v[96:99], v[68:69], off offset:800
	global_load_dwordx4 v[100:103], v[74:75], off offset:768
	global_load_dwordx4 v[104:107], v[74:75], off offset:800
	global_load_dwordx4 v[108:111], v[72:73], off offset:768
	global_load_dwordx4 v[112:115], v[72:73], off offset:800
	global_load_dwordx4 v[116:119], v[70:71], off offset:768
	global_load_dwordx4 v[120:123], v[70:71], off offset:800
	s_waitcnt vmcnt(16)
	v_mfma_f32_32x32x16_bf16 v[0:15], v[124:127], v[144:147], v[0:15]
	v_mfma_f32_32x32x16_bf16 v[48:63], v[124:127], v[152:155], v[48:63]
	v_mfma_f32_32x32x16_bf16 v[16:31], v[132:135], v[144:147], v[16:31]
	v_mfma_f32_32x32x16_bf16 v[32:47], v[132:135], v[152:155], v[32:47]
	v_mfma_f32_32x32x16_bf16 v[0:15], v[128:131], v[148:151], v[0:15]
	v_mfma_f32_32x32x16_bf16 v[48:63], v[128:131], v[156:159], v[48:63]
	v_mfma_f32_32x32x16_bf16 v[16:31], v[136:139], v[148:151], v[16:31]
	v_mfma_f32_32x32x16_bf16 v[32:47], v[136:139], v[156:159], v[32:47]
	global_load_dwordx4 v[124:127], v[68:69], off offset:832
	global_load_dwordx4 v[128:131], v[68:69], off offset:864
	global_load_dwordx4 v[132:135], v[74:75], off offset:832
	global_load_dwordx4 v[136:139], v[74:75], off offset:864
	global_load_dwordx4 v[144:147], v[72:73], off offset:832
	global_load_dwordx4 v[148:151], v[72:73], off offset:864
	global_load_dwordx4 v[152:155], v[70:71], off offset:832
	global_load_dwordx4 v[156:159], v[70:71], off offset:864
	s_waitcnt vmcnt(16)
	v_mfma_f32_32x32x16_bf16 v[0:15], v[160:163], v[176:179], v[0:15]
	v_mfma_f32_32x32x16_bf16 v[48:63], v[160:163], v[184:187], v[48:63]
	v_mfma_f32_32x32x16_bf16 v[16:31], v[168:171], v[176:179], v[16:31]
	v_mfma_f32_32x32x16_bf16 v[32:47], v[168:171], v[184:187], v[32:47]
	v_mfma_f32_32x32x16_bf16 v[0:15], v[164:167], v[180:183], v[0:15]
	v_mfma_f32_32x32x16_bf16 v[48:63], v[164:167], v[188:191], v[48:63]
	v_mfma_f32_32x32x16_bf16 v[16:31], v[172:175], v[180:183], v[16:31]
	v_mfma_f32_32x32x16_bf16 v[32:47], v[172:175], v[188:191], v[32:47]
	global_load_dwordx4 v[160:163], v[68:69], off offset:896
	global_load_dwordx4 v[164:167], v[68:69], off offset:928
	global_load_dwordx4 v[168:171], v[74:75], off offset:896
	global_load_dwordx4 v[172:175], v[74:75], off offset:928
	global_load_dwordx4 v[176:179], v[72:73], off offset:896
	global_load_dwordx4 v[180:183], v[72:73], off offset:928
	global_load_dwordx4 v[184:187], v[70:71], off offset:896
	global_load_dwordx4 v[188:191], v[70:71], off offset:928
	s_waitcnt vmcnt(16)
	v_mfma_f32_32x32x16_bf16 v[0:15], v[92:95], v[108:111], v[0:15]
	v_mfma_f32_32x32x16_bf16 v[48:63], v[92:95], v[116:119], v[48:63]
	v_mfma_f32_32x32x16_bf16 v[16:31], v[100:103], v[108:111], v[16:31]
	v_mfma_f32_32x32x16_bf16 v[32:47], v[100:103], v[116:119], v[32:47]
	v_mfma_f32_32x32x16_bf16 v[0:15], v[96:99], v[112:115], v[0:15]
	v_mfma_f32_32x32x16_bf16 v[48:63], v[96:99], v[120:123], v[48:63]
	v_mfma_f32_32x32x16_bf16 v[16:31], v[104:107], v[112:115], v[16:31]
	v_mfma_f32_32x32x16_bf16 v[32:47], v[104:107], v[120:123], v[32:47]
	global_load_dwordx4 v[92:95], v[68:69], off offset:960
	global_load_dwordx4 v[96:99], v[68:69], off offset:992
	global_load_dwordx4 v[100:103], v[74:75], off offset:960
	global_load_dwordx4 v[104:107], v[74:75], off offset:992
	global_load_dwordx4 v[108:111], v[72:73], off offset:960
	global_load_dwordx4 v[112:115], v[72:73], off offset:992
	global_load_dwordx4 v[116:119], v[70:71], off offset:960
	global_load_dwordx4 v[120:123], v[70:71], off offset:992
	s_waitcnt vmcnt(16)
	v_mfma_f32_32x32x16_bf16 v[0:15], v[124:127], v[144:147], v[0:15]
	v_mfma_f32_32x32x16_bf16 v[48:63], v[124:127], v[152:155], v[48:63]
	v_mfma_f32_32x32x16_bf16 v[16:31], v[132:135], v[144:147], v[16:31]
	v_mfma_f32_32x32x16_bf16 v[32:47], v[132:135], v[152:155], v[32:47]
	v_mfma_f32_32x32x16_bf16 v[0:15], v[128:131], v[148:151], v[0:15]
	v_mfma_f32_32x32x16_bf16 v[48:63], v[128:131], v[156:159], v[48:63]
	v_mfma_f32_32x32x16_bf16 v[16:31], v[136:139], v[148:151], v[16:31]
	v_mfma_f32_32x32x16_bf16 v[32:47], v[136:139], v[156:159], v[32:47]
	s_waitcnt vmcnt(8)
	v_mfma_f32_32x32x16_bf16 v[0:15], v[160:163], v[176:179], v[0:15]
	v_mfma_f32_32x32x16_bf16 v[48:63], v[160:163], v[184:187], v[48:63]
	v_mfma_f32_32x32x16_bf16 v[16:31], v[168:171], v[176:179], v[16:31]
	v_mfma_f32_32x32x16_bf16 v[32:47], v[168:171], v[184:187], v[32:47]
	v_mfma_f32_32x32x16_bf16 v[0:15], v[164:167], v[180:183], v[0:15]
	v_mfma_f32_32x32x16_bf16 v[48:63], v[164:167], v[188:191], v[48:63]
	v_mfma_f32_32x32x16_bf16 v[16:31], v[172:175], v[180:183], v[16:31]
	v_mfma_f32_32x32x16_bf16 v[32:47], v[172:175], v[188:191], v[32:47]
	s_waitcnt vmcnt(0)
	v_mfma_f32_32x32x16_bf16 v[0:15], v[92:95], v[108:111], v[0:15]
	v_mfma_f32_32x32x16_bf16 v[48:63], v[92:95], v[116:119], v[48:63]
	v_mfma_f32_32x32x16_bf16 v[16:31], v[100:103], v[108:111], v[16:31]
	v_mfma_f32_32x32x16_bf16 v[32:47], v[100:103], v[116:119], v[32:47]
	v_mfma_f32_32x32x16_bf16 v[0:15], v[96:99], v[112:115], v[0:15]
	v_mfma_f32_32x32x16_bf16 v[48:63], v[96:99], v[120:123], v[48:63]
	v_mfma_f32_32x32x16_bf16 v[16:31], v[104:107], v[112:115], v[16:31]
	v_mfma_f32_32x32x16_bf16 v[32:47], v[104:107], v[120:123], v[32:47]
	s_nop 15
	ds_write2_b32 v77, v0, v48 offset1:32
	ds_write2_b32 v77, v1, v49 offset0:64 offset1:96
	ds_write2_b32 v77, v2, v50 offset0:128 offset1:160
	ds_write2_b32 v77, v3, v51 offset0:192 offset1:224
	v_add_u32_e32 v0, 0x800, v77
	ds_write2_b32 v0, v4, v52 offset1:32
	ds_write2_b32 v0, v5, v53 offset0:64 offset1:96
	ds_write2_b32 v0, v6, v54 offset0:128 offset1:160
	ds_write2_b32 v0, v7, v55 offset0:192 offset1:224
	v_add_u32_e32 v0, 0x1000, v77
	ds_write2_b32 v0, v8, v56 offset1:32
	ds_write2_b32 v0, v9, v57 offset0:64 offset1:96
	ds_write2_b32 v0, v10, v58 offset0:128 offset1:160
	ds_write2_b32 v0, v11, v59 offset0:192 offset1:224
	v_add_u32_e32 v0, 0x1800, v77
	ds_write2_b32 v0, v12, v60 offset1:32
	ds_write2_b32 v0, v13, v61 offset0:64 offset1:96
	ds_write2_b32 v0, v14, v62 offset0:128 offset1:160
	ds_write2_b32 v0, v15, v63 offset0:192 offset1:224
	v_add_u32_e32 v0, 0x2000, v77
	ds_write2_b32 v0, v16, v32 offset1:32
	ds_write2_b32 v0, v17, v33 offset0:64 offset1:96
	ds_write2_b32 v0, v18, v34 offset0:128 offset1:160
	ds_write2_b32 v0, v19, v35 offset0:192 offset1:224
	v_add_u32_e32 v0, 0x2800, v77
	ds_write2_b32 v0, v20, v36 offset1:32
	ds_write2_b32 v0, v21, v37 offset0:64 offset1:96
	ds_write2_b32 v0, v22, v38 offset0:128 offset1:160
	ds_write2_b32 v0, v23, v39 offset0:192 offset1:224
	v_add_u32_e32 v0, 0x3000, v77
	ds_write2_b32 v0, v24, v40 offset1:32
	ds_write2_b32 v0, v25, v41 offset0:64 offset1:96
	ds_write2_b32 v0, v26, v42 offset0:128 offset1:160
	ds_write2_b32 v0, v27, v43 offset0:192 offset1:224
	v_add_u32_e32 v0, 0x3800, v77
	ds_write2_b32 v0, v28, v44 offset1:32
	ds_write2_b32 v0, v29, v45 offset0:64 offset1:96
	ds_write2_b32 v0, v30, v46 offset0:128 offset1:160
	ds_write2_b32 v0, v31, v47 offset0:192 offset1:224
	v_add_u32_e32 v4, s36, v78
	v_ashrrev_i32_e32 v5, 31, v4
	v_or_b32_e32 v0, s37, v79
	v_lshlrev_b64 v[2:3], 11, v[4:5]
	v_lshl_add_u64 v[6:7], s[30:31], 0, v[2:3]
	v_ashrrev_i32_e32 v1, 31, v0
	v_lshl_add_u64 v[6:7], v[0:1], 1, v[6:7]
	s_waitcnt lgkmcnt(0)
	s_barrier
	global_load_dwordx4 v[10:13], v[6:7], off
	ds_read_b128 v[6:9], v80
	ds_read_b128 v[14:17], v80 offset:16
	ds_read_b128 v[18:21], v80 offset:18432
	ds_read_b128 v[22:25], v80 offset:18448
	ds_read_b128 v[26:29], v80 offset:36864
	ds_read_b128 v[30:33], v80 offset:36880
	ds_read_b128 v[34:37], v80 offset:55296
	ds_read_b128 v[38:41], v80 offset:55312
	ds_read_b128 v[42:45], v84
	ds_read_b128 v[46:49], v85
	ds_read_b128 v[50:53], v86
	ds_read_b128 v[54:57], v87
	ds_read_b128 v[58:61], v88
	ds_read_b128 v[68:71], v89
	ds_read_b128 v[72:75], v90
	ds_read_b128 v[92:95], v91
	s_waitcnt lgkmcnt(14)
	v_pk_add_f32 v[8:9], v[8:9], 0 op_sel_hi:[1,0]
	v_pk_add_f32 v[6:7], v[6:7], 0 op_sel_hi:[1,0]
	s_waitcnt lgkmcnt(13)
	v_pk_add_f32 v[8:9], v[8:9], v[20:21]
	v_pk_add_f32 v[6:7], v[6:7], v[18:19]
	s_waitcnt lgkmcnt(11)
	v_pk_add_f32 v[8:9], v[8:9], v[28:29]
	v_pk_add_f32 v[6:7], v[6:7], v[26:27]
	s_waitcnt lgkmcnt(9)
	v_pk_add_f32 v[8:9], v[8:9], v[36:37]
	v_pk_add_f32 v[6:7], v[6:7], v[34:35]
	s_waitcnt lgkmcnt(7)
	v_pk_add_f32 v[8:9], v[8:9], v[44:45]
	v_pk_add_f32 v[6:7], v[6:7], v[42:43]
	s_waitcnt lgkmcnt(5)
	v_pk_add_f32 v[8:9], v[8:9], v[52:53]
	v_pk_add_f32 v[6:7], v[6:7], v[50:51]
	s_waitcnt lgkmcnt(3)
	v_pk_add_f32 v[8:9], v[8:9], v[60:61]
	v_pk_add_f32 v[6:7], v[6:7], v[58:59]
	s_waitcnt lgkmcnt(1)
	v_pk_add_f32 v[8:9], v[8:9], v[74:75]
	v_pk_add_f32 v[6:7], v[6:7], v[72:73]
	s_waitcnt vmcnt(0)
	v_lshlrev_b32_e32 v18, 16, v10
	v_and_b32_e32 v19, 0xffff0000, v10
	v_lshlrev_b32_e32 v10, 16, v11
	v_and_b32_e32 v11, 0xffff0000, v11
	v_pk_add_f32 v[8:9], v[8:9], v[10:11]
	v_pk_add_f32 v[10:11], v[14:15], 0 op_sel_hi:[1,0]
	v_lshlrev_b32_e32 v14, 16, v12
	v_pk_add_f32 v[10:11], v[10:11], v[22:23]
	v_and_b32_e32 v15, 0xffff0000, v12
	v_pk_add_f32 v[10:11], v[10:11], v[30:31]
	v_pk_add_f32 v[6:7], v[6:7], v[18:19]
	v_pk_add_f32 v[10:11], v[10:11], v[38:39]
	v_lshlrev_b32_e32 v12, 16, v13
	v_pk_add_f32 v[10:11], v[10:11], v[46:47]
	v_and_b32_e32 v13, 0xffff0000, v13
	v_pk_add_f32 v[10:11], v[10:11], v[54:55]
	s_nop 0
	v_pk_add_f32 v[10:11], v[10:11], v[68:69]
	s_waitcnt lgkmcnt(0)
	v_pk_add_f32 v[10:11], v[10:11], v[92:93]
	s_nop 0
	v_pk_add_f32 v[10:11], v[10:11], v[14:15]
	v_pk_add_f32 v[14:15], v[16:17], 0 op_sel_hi:[1,0]
	v_pk_mul_f32 v[16:17], v[8:9], v[8:9]
	v_pk_add_f32 v[14:15], v[14:15], v[24:25]
	v_pk_mul_f32 v[18:19], v[10:11], v[10:11]
	v_pk_add_f32 v[14:15], v[14:15], v[32:33]
	s_nop 0
	v_pk_add_f32 v[14:15], v[14:15], v[40:41]
	s_nop 0
	v_pk_add_f32 v[14:15], v[14:15], v[48:49]
	s_nop 0
	v_pk_add_f32 v[14:15], v[14:15], v[56:57]
	s_nop 0
	v_pk_add_f32 v[14:15], v[14:15], v[70:71]
	s_nop 0
	v_pk_add_f32 v[14:15], v[14:15], v[94:95]
	s_nop 0
	v_pk_add_f32 v[12:13], v[14:15], v[12:13]
	v_pk_mul_f32 v[14:15], v[6:7], v[6:7]
	v_pk_mul_f32 v[20:21], v[12:13], v[12:13]
	v_add_f32_e32 v14, v14, v15
	v_add_f32_e32 v14, v16, v14
	v_add_f32_e32 v14, v17, v14
	v_add_f32_e32 v14, v18, v14
	v_add_f32_e32 v14, v19, v14
	v_add_f32_e32 v14, v20, v14
	v_add_f32_e32 v14, v21, v14
	ds_bpermute_b32 v15, v81, v14
	s_waitcnt lgkmcnt(0)
	v_add_f32_e32 v14, v14, v15
	ds_bpermute_b32 v15, v82, v14
	s_waitcnt lgkmcnt(0)
	v_add_f32_e32 v14, v14, v15
	ds_bpermute_b32 v15, v83, v14
	s_and_saveexec_b64 s[36:37], s[38:39]
	s_cbranch_execz .LBB0_1256
	v_lshl_add_u64 v[4:5], v[4:5], 2, s[22:23]
	s_waitcnt lgkmcnt(0)
	v_add_f32_e32 v14, v14, v15
	global_atomic_add_f32 v[4:5], v14, off
	s_branch .LBB0_1256
